# prep SSD conv sliding-window loads issued up front; GEMM-tail transposes use 4 waves per idle workgroup
# speedup vs baseline: 1.0474x; 1.0016x over previous
; __device__ __forceinline__ float silu_(float x) { return x * sigmoid_(x); }
; __device__ __forceinline__ unsigned pk2(float lo, float hi) { return f2bf(lo) | (f2bf(hi) << 16); }
; __device__ __forceinline__ f32x4 ld_bf4(const bf16* p) { const u32x2 w = *(const u32x2*)p; return (f32x4){__builtin_bit_cast(float, w.x << 16), __builtin_bit_cast(float, w.x & 0xffff0000u), __builtin_bit_cast(float, w.y << 16), __builtin_bit_cast(float, w.y & 0xffff0000u)}; }
; __device__ __forceinline__ void prep_phase(const Params& P, float* L, int l) {
;     ...
;           int t0, len; if (row0 < MLAT) { t0 = row0 & (TL - 1); len = TL; } else { t0 = (row0 - MLAT) & (TC - 1); len = TC; }
;           const f32x4 w0 = *(const f32x4*)(cw + c4), w1 = *(const f32x4*)(cw + 768 + c4), w2 = *(const f32x4*)(cw + 2 * 768 + c4), w3 = *(const f32x4*)(cw + 3 * 768 + c4), bb = *(const f32x4*)(cb + c4);
;           const bf16* up = (const bf16*)(P.ws + WS_UG) + (size_t)row0 * NUG + G_SSD_XBC + c4;
;           const f32x4 z4 = {0.f, 0.f, 0.f, 0.f};
;           f32x4 xm1 = (t0 > 0) ? ld_bf4(up - NUG) : z4, x0 = ld_bf4(up), x1 = ld_bf4(up + NUG);
; #pragma unroll
;           for (int r = 0; r < 16; ++r) {
;               const f32x4 x2 = (t0 + r + 2 < len) ? ld_bf4(up + (size_t)(r + 2) * NUG) : z4;
;               f32x4 v = bb + xm1 * w0 + x0 * w1 + x1 * w2 + x2 * w3;
;               v.x = silu_(v.x); v.y = silu_(v.y); v.z = silu_(v.z); v.w = silu_(v.w);
;               { u32x2 w_; w_.x = pk2(v.x, v.y); w_.y = pk2(v.z, v.w); *(u32x2*)(XBC + (size_t)(row0 + r) * 768 + c4) = w_; }
;               xm1 = x0; x0 = x1; x1 = x2;
;           } } }
.LBB0_220:
	s_or_b64 exec, exec, s[20:21]
	v_add_co_u32_e32 v34, vcc, 0x2000, v24
	global_load_dwordx2 v[30:31], v[24:25], off
	s_nop 0
	v_addc_co_u32_e32 v35, vcc, 0, v25, vcc
	global_load_dwordx2 v[40:41], v[34:35], off offset:2560
	v_cndmask_b32_e64 v53, v192, v193, s[6:7]
	v_add_u32_e32 v94, 2, v51
	v_cmp_lt_u32_e32 vcc, v94, v53
	s_and_saveexec_b64 s[98:99], vcc
	v_add_co_u32_e32 v92, vcc, 0x5400, v24
	s_nop 1
	v_addc_co_u32_e32 v93, vcc, 0, v25, vcc
	global_load_dwordx2 v[60:61], v[92:93], off
	s_or_b64 exec, exec, s[98:99]
	v_add_u32_e32 v94, 3, v51
	v_cmp_lt_u32_e32 vcc, v94, v53
	s_and_saveexec_b64 s[98:99], vcc
	v_add_co_u32_e32 v92, vcc, 0x7e00, v24
	s_nop 1
	v_addc_co_u32_e32 v93, vcc, 0, v25, vcc
	global_load_dwordx2 v[62:63], v[92:93], off
	s_or_b64 exec, exec, s[98:99]
	v_add_u32_e32 v94, 4, v51
	v_cmp_lt_u32_e32 vcc, v94, v53
	s_and_saveexec_b64 s[98:99], vcc
	v_add_co_u32_e32 v92, vcc, 0xa800, v24
	s_nop 1
	v_addc_co_u32_e32 v93, vcc, 0, v25, vcc
	global_load_dwordx2 v[64:65], v[92:93], off
	s_or_b64 exec, exec, s[98:99]
	v_add_u32_e32 v94, 5, v51
	v_cmp_lt_u32_e32 vcc, v94, v53
	s_and_saveexec_b64 s[98:99], vcc
	v_add_co_u32_e32 v92, vcc, 0xd200, v24
	s_nop 1
	v_addc_co_u32_e32 v93, vcc, 0, v25, vcc
	global_load_dwordx2 v[66:67], v[92:93], off
	s_or_b64 exec, exec, s[98:99]
	v_add_u32_e32 v94, 6, v51
	v_cmp_lt_u32_e32 vcc, v94, v53
	s_and_saveexec_b64 s[98:99], vcc
	v_add_co_u32_e32 v92, vcc, 0xfc00, v24
	s_nop 1
	v_addc_co_u32_e32 v93, vcc, 0, v25, vcc
	global_load_dwordx2 v[68:69], v[92:93], off
	s_or_b64 exec, exec, s[98:99]
	v_add_u32_e32 v94, 7, v51
	v_cmp_lt_u32_e32 vcc, v94, v53
	s_and_saveexec_b64 s[98:99], vcc
	v_add_co_u32_e32 v92, vcc, 0x12600, v24
	s_nop 1
	v_addc_co_u32_e32 v93, vcc, 0, v25, vcc
	global_load_dwordx2 v[70:71], v[92:93], off
	s_or_b64 exec, exec, s[98:99]
	v_add_u32_e32 v94, 8, v51
	v_cmp_lt_u32_e32 vcc, v94, v53
	s_and_saveexec_b64 s[98:99], vcc
	v_add_co_u32_e32 v92, vcc, 0x15000, v24
	s_nop 1
	v_addc_co_u32_e32 v93, vcc, 0, v25, vcc
	global_load_dwordx2 v[72:73], v[92:93], off
	s_or_b64 exec, exec, s[98:99]
	v_add_u32_e32 v94, 9, v51
	v_cmp_lt_u32_e32 vcc, v94, v53
	s_and_saveexec_b64 s[98:99], vcc
	v_add_co_u32_e32 v92, vcc, 0x17a00, v24
	s_nop 1
	v_addc_co_u32_e32 v93, vcc, 0, v25, vcc
	global_load_dwordx2 v[74:75], v[92:93], off
	s_or_b64 exec, exec, s[98:99]
	v_add_u32_e32 v94, 10, v51
	v_cmp_lt_u32_e32 vcc, v94, v53
	s_and_saveexec_b64 s[98:99], vcc
	v_add_co_u32_e32 v92, vcc, 0x1a400, v24
	s_nop 1
	v_addc_co_u32_e32 v93, vcc, 0, v25, vcc
	global_load_dwordx2 v[76:77], v[92:93], off
	s_or_b64 exec, exec, s[98:99]
	v_add_u32_e32 v94, 11, v51
	v_cmp_lt_u32_e32 vcc, v94, v53
	s_and_saveexec_b64 s[98:99], vcc
	v_add_co_u32_e32 v92, vcc, 0x1ce00, v24
	s_nop 1
	v_addc_co_u32_e32 v93, vcc, 0, v25, vcc
	global_load_dwordx2 v[78:79], v[92:93], off
	s_or_b64 exec, exec, s[98:99]
	v_add_u32_e32 v94, 12, v51
	v_cmp_lt_u32_e32 vcc, v94, v53
	s_and_saveexec_b64 s[98:99], vcc
	v_add_co_u32_e32 v92, vcc, 0x1f800, v24
	s_nop 1
	v_addc_co_u32_e32 v93, vcc, 0, v25, vcc
	global_load_dwordx2 v[80:81], v[92:93], off
	s_or_b64 exec, exec, s[98:99]
	v_add_u32_e32 v94, 13, v51
	v_cmp_lt_u32_e32 vcc, v94, v53
	s_and_saveexec_b64 s[98:99], vcc
	v_add_co_u32_e32 v92, vcc, 0x22200, v24
	s_nop 1
	v_addc_co_u32_e32 v93, vcc, 0, v25, vcc
	global_load_dwordx2 v[82:83], v[92:93], off
	s_or_b64 exec, exec, s[98:99]
	v_add_u32_e32 v94, 14, v51
	v_cmp_lt_u32_e32 vcc, v94, v53
	s_and_saveexec_b64 s[98:99], vcc
	v_add_co_u32_e32 v92, vcc, 0x24c00, v24
	s_nop 1
	v_addc_co_u32_e32 v93, vcc, 0, v25, vcc
	global_load_dwordx2 v[84:85], v[92:93], off
	s_or_b64 exec, exec, s[98:99]
	v_add_u32_e32 v94, 15, v51
	v_cmp_lt_u32_e32 vcc, v94, v53
	s_and_saveexec_b64 s[98:99], vcc
	v_add_co_u32_e32 v92, vcc, 0x27600, v24
	s_nop 1
	v_addc_co_u32_e32 v93, vcc, 0, v25, vcc
	global_load_dwordx2 v[86:87], v[92:93], off
	s_or_b64 exec, exec, s[98:99]
	v_add_u32_e32 v94, 16, v51
	v_cmp_lt_u32_e32 vcc, v94, v53
	s_and_saveexec_b64 s[98:99], vcc
	v_add_co_u32_e32 v92, vcc, 0x2a000, v24
	s_nop 1
	v_addc_co_u32_e32 v93, vcc, 0, v25, vcc
	global_load_dwordx2 v[88:89], v[92:93], off
	s_or_b64 exec, exec, s[98:99]
	v_add_u32_e32 v94, 17, v51
	v_cmp_lt_u32_e32 vcc, v94, v53
	s_and_saveexec_b64 s[98:99], vcc
	v_add_co_u32_e32 v92, vcc, 0x2ca00, v24
	s_nop 1
	v_addc_co_u32_e32 v93, vcc, 0, v25, vcc
	global_load_dwordx2 v[90:91], v[92:93], off
	s_or_b64 exec, exec, s[98:99]
	v_or_b32_e32 v33, 2, v51
	v_cmp_lt_u32_e32 vcc, v33, v53
	v_mov_b32_e32 v33, 0
	v_mov_b32_e32 v34, 0
	v_mov_b32_e32 v35, 0
	s_and_saveexec_b64 s[6:7], vcc
	s_cbranch_execz .LBB0_222
	s_waitcnt vmcnt(15)
	v_lshlrev_b32_e32 v32, 16, v60
	v_and_b32_e32 v33, 0xffff0000, v60
	v_lshlrev_b32_e32 v34, 16, v61
	v_and_b32_e32 v35, 0xffff0000, v61
; __device__ __forceinline__ float silu_(float x) { return x * sigmoid_(x); }
; __device__ __forceinline__ unsigned pk2(float lo, float hi) { return f2bf(lo) | (f2bf(hi) << 16); }
; __device__ __forceinline__ f32x4 ld_bf4(const bf16* p) { const u32x2 w = *(const u32x2*)p; return (f32x4){__builtin_bit_cast(float, w.x << 16), __builtin_bit_cast(float, w.x & 0xffff0000u), __builtin_bit_cast(float, w.y << 16), __builtin_bit_cast(float, w.y & 0xffff0000u)}; }
; __device__ __forceinline__ void prep_phase(const Params& P, float* L, int l) {
;     ...
;           f32x4 xm1 = (t0 > 0) ? ld_bf4(up - NUG) : z4, x0 = ld_bf4(up), x1 = ld_bf4(up + NUG);
; #pragma unroll
;           for (int r = 0; r < 16; ++r) {
;               const f32x4 x2 = (t0 + r + 2 < len) ? ld_bf4(up + (size_t)(r + 2) * NUG) : z4;
;               f32x4 v = bb + xm1 * w0 + x0 * w1 + x1 * w2 + x2 * w3;
;               v.x = silu_(v.x); v.y = silu_(v.y); v.z = silu_(v.z); v.w = silu_(v.w);
;               { u32x2 w_; w_.x = pk2(v.x, v.y); w_.y = pk2(v.z, v.w); *(u32x2*)(XBC + (size_t)(row0 + r) * 768 + c4) = w_; }
;               xm1 = x0; x0 = x1; x1 = x2;
.LBB0_222:
	s_or_b64 exec, exec, s[6:7]
	s_waitcnt vmcnt(16)
	v_lshlrev_b32_e32 v36, 16, v30
	v_and_b32_e32 v37, 0xffff0000, v30
	v_pk_fma_f32 v[28:29], v[16:17], v[28:29], v[20:21]
	v_lshlrev_b32_e32 v44, 16, v31
	v_and_b32_e32 v45, 0xffff0000, v31
	s_waitcnt vmcnt(16)
	v_lshlrev_b32_e32 v30, 16, v40
	v_and_b32_e32 v31, 0xffff0000, v40
	v_pk_fma_f32 v[38:39], v[18:19], v[38:39], v[22:23]
	v_pk_fma_f32 v[28:29], v[8:9], v[36:37], v[28:29]
	v_lshlrev_b32_e32 v40, 16, v41
	v_and_b32_e32 v41, 0xffff0000, v41
	v_pk_fma_f32 v[38:39], v[10:11], v[44:45], v[38:39]
	v_pk_fma_f32 v[28:29], v[12:13], v[30:31], v[28:29]
	v_pk_fma_f32 v[38:39], v[14:15], v[40:41], v[38:39]
	v_pk_fma_f32 v[28:29], v[4:5], v[32:33], v[28:29]
	v_pk_fma_f32 v[38:39], v[6:7], v[34:35], v[38:39]
	v_mul_f32_e32 v43, 0xbfb8aa3b, v29
	v_mul_f32_e32 v42, 0xbfb8aa3b, v28
	v_exp_f32_e32 v43, v43
	v_mul_f32_e32 v46, 0xbfb8aa3b, v38
	v_exp_f32_e32 v42, v42
	v_exp_f32_e32 v47, v46
	v_mul_f32_e32 v46, 0xbfb8aa3b, v39
	v_exp_f32_e32 v48, v46
	v_add_f32_e32 v43, 1.0, v43
	v_add_f32_e32 v42, 1.0, v42
	v_rcp_f32_e32 v46, v43
	v_add_f32_e32 v43, 1.0, v47
	v_rcp_f32_e32 v42, v42
	v_rcp_f32_e32 v43, v43
	v_add_f32_e32 v47, 1.0, v48
	v_rcp_f32_e32 v47, v47
	v_mov_b32_e32 v48, v28
	v_mov_b32_e32 v49, v38
	v_pk_mul_f32 v[42:43], v[48:49], v[42:43]
	v_mov_b32_e32 v38, v29
	v_pk_mul_f32 v[28:29], v[38:39], v[46:47]
	v_and_b32_sdwa v38, v43, v173 dst_sel:DWORD dst_unused:UNUSED_PAD src0_sel:WORD_1 src1_sel:DWORD
	v_and_b32_sdwa v39, v42, v173 dst_sel:DWORD dst_unused:UNUSED_PAD src0_sel:WORD_1 src1_sel:DWORD
	v_add3_u32 v39, v42, v39, s71
	v_add3_u32 v38, v43, v38, s71
	v_and_b32_sdwa v42, v29, v173 dst_sel:DWORD dst_unused:UNUSED_PAD src0_sel:WORD_1 src1_sel:DWORD
	v_and_b32_sdwa v43, v28, v173 dst_sel:DWORD dst_unused:UNUSED_PAD src0_sel:WORD_1 src1_sel:DWORD
	v_add3_u32 v29, v29, v42, s71
	v_add3_u32 v28, v28, v43, s71
	v_lshl_add_u64 v[26:27], v[26:27], 1, s[4:5]
	v_and_b32_e32 v29, 0xffff0000, v29
	v_and_b32_e32 v28, 0xffff0000, v28
	s_movk_i32 s3, 0x600
	v_or_b32_sdwa v29, v29, v38 dst_sel:DWORD dst_unused:UNUSED_PAD src0_sel:DWORD src1_sel:WORD_1
	v_or_b32_sdwa v28, v28, v39 dst_sel:DWORD dst_unused:UNUSED_PAD src0_sel:DWORD src1_sel:WORD_1
	v_mad_i64_i32 v[38:39], s[6:7], v50, s3, v[26:27]
	global_store_dwordx2 v[38:39], v[28:29], off
	v_or_b32_e32 v28, 3, v51
	v_cmp_lt_u32_e32 vcc, v28, v53
	v_mov_b32_e32 v28, 0
	v_mov_b32_e32 v38, 0
	v_mov_b32_e32 v39, 0
	v_mov_b32_e32 v42, 0
	v_mov_b32_e32 v43, 0
	s_and_saveexec_b64 s[6:7], vcc
	s_cbranch_execz .LBB0_224
	s_waitcnt vmcnt(15)
	v_lshlrev_b32_e32 v38, 16, v62
	v_and_b32_e32 v39, 0xffff0000, v62
	v_lshlrev_b32_e32 v42, 16, v63
	v_and_b32_e32 v43, 0xffff0000, v63
.LBB0_224:
	s_or_b64 exec, exec, s[6:7]
	v_pk_fma_f32 v[36:37], v[16:17], v[36:37], v[20:21]
	v_pk_fma_f32 v[44:45], v[18:19], v[44:45], v[22:23]
	v_pk_fma_f32 v[36:37], v[8:9], v[30:31], v[36:37]
	v_pk_fma_f32 v[44:45], v[10:11], v[40:41], v[44:45]
	v_pk_fma_f32 v[36:37], v[12:13], v[32:33], v[36:37]
	v_pk_fma_f32 v[44:45], v[14:15], v[34:35], v[44:45]
	v_pk_fma_f32 v[36:37], v[4:5], v[38:39], v[36:37]
	v_pk_fma_f32 v[44:45], v[6:7], v[42:43], v[44:45]
	v_mul_f32_e32 v29, 0xbfb8aa3b, v36
	v_exp_f32_e32 v29, v29
	v_mul_f32_e32 v46, 0xbfb8aa3b, v37
	v_exp_f32_e32 v47, v46
	v_mul_f32_e32 v48, 0xbfb8aa3b, v45
	v_add_f32_e32 v29, 1.0, v29
	v_rcp_f32_e32 v46, v29
	v_add_f32_e32 v29, 1.0, v47
	v_mul_f32_e32 v47, 0xbfb8aa3b, v44
	v_exp_f32_e32 v47, v47
	v_exp_f32_e32 v49, v48
	v_rcp_f32_e32 v48, v29
	v_mov_b32_e32 v54, v36
	v_add_f32_e32 v29, 1.0, v47
	v_rcp_f32_e32 v47, v29
	v_add_f32_e32 v29, 1.0, v49
	v_rcp_f32_e32 v49, v29
	v_mov_b32_e32 v55, v44
	v_mov_b32_e32 v44, v37
	v_pk_mul_f32 v[46:47], v[54:55], v[46:47]
	v_pk_mul_f32 v[36:37], v[44:45], v[48:49]
	v_and_b32_sdwa v44, v46, v173 dst_sel:DWORD dst_unused:UNUSED_PAD src0_sel:WORD_1 src1_sel:DWORD
	v_and_b32_sdwa v45, v37, v173 dst_sel:DWORD dst_unused:UNUSED_PAD src0_sel:WORD_1 src1_sel:DWORD
	v_and_b32_sdwa v29, v47, v173 dst_sel:DWORD dst_unused:UNUSED_PAD src0_sel:WORD_1 src1_sel:DWORD
	v_add3_u32 v44, v46, v44, s71
	v_and_b32_sdwa v46, v36, v173 dst_sel:DWORD dst_unused:UNUSED_PAD src0_sel:WORD_1 src1_sel:DWORD
	v_add3_u32 v37, v37, v45, s71
	v_add3_u32 v29, v47, v29, s71
	v_add3_u32 v36, v36, v46, s71
	v_and_b32_e32 v37, 0xffff0000, v37
	v_and_b32_e32 v36, 0xffff0000, v36
	v_or_b32_sdwa v37, v37, v29 dst_sel:DWORD dst_unused:UNUSED_PAD src0_sel:DWORD src1_sel:WORD_1
	v_or_b32_e32 v29, 1, v50
	v_or_b32_sdwa v36, v36, v44 dst_sel:DWORD dst_unused:UNUSED_PAD src0_sel:DWORD src1_sel:WORD_1
	v_mad_i64_i32 v[44:45], s[6:7], v29, s3, v[26:27]
	v_or_b32_e32 v29, 4, v51
	global_store_dwordx2 v[44:45], v[36:37], off
	v_cmp_lt_u32_e32 vcc, v29, v53
	v_mov_b32_e32 v29, 0
	v_mov_b32_e32 v36, 0
	v_mov_b32_e32 v37, 0
	s_and_saveexec_b64 s[6:7], vcc
	s_cbranch_execz .LBB0_226
	s_waitcnt vmcnt(15)
	v_lshlrev_b32_e32 v28, 16, v64
	v_and_b32_e32 v29, 0xffff0000, v64
	v_lshlrev_b32_e32 v36, 16, v65
	v_and_b32_e32 v37, 0xffff0000, v65
; __device__ __forceinline__ float silu_(float x) { return x * sigmoid_(x); }
; __device__ __forceinline__ unsigned pk2(float lo, float hi) { return f2bf(lo) | (f2bf(hi) << 16); }
; __device__ __forceinline__ f32x4 ld_bf4(const bf16* p) { const u32x2 w = *(const u32x2*)p; return (f32x4){__builtin_bit_cast(float, w.x << 16), __builtin_bit_cast(float, w.x & 0xffff0000u), __builtin_bit_cast(float, w.y << 16), __builtin_bit_cast(float, w.y & 0xffff0000u)}; }
; __device__ __forceinline__ void prep_phase(const Params& P, float* L, int l) {
;     ...
;           f32x4 xm1 = (t0 > 0) ? ld_bf4(up - NUG) : z4, x0 = ld_bf4(up), x1 = ld_bf4(up + NUG);
; #pragma unroll
;           for (int r = 0; r < 16; ++r) {
;               const f32x4 x2 = (t0 + r + 2 < len) ? ld_bf4(up + (size_t)(r + 2) * NUG) : z4;
;               f32x4 v = bb + xm1 * w0 + x0 * w1 + x1 * w2 + x2 * w3;
;               v.x = silu_(v.x); v.y = silu_(v.y); v.z = silu_(v.z); v.w = silu_(v.w);
;               { u32x2 w_; w_.x = pk2(v.x, v.y); w_.y = pk2(v.z, v.w); *(u32x2*)(XBC + (size_t)(row0 + r) * 768 + c4) = w_; }
;               xm1 = x0; x0 = x1; x1 = x2;
.LBB0_226:
	s_or_b64 exec, exec, s[6:7]
	v_pk_fma_f32 v[30:31], v[16:17], v[30:31], v[20:21]
	v_pk_fma_f32 v[40:41], v[18:19], v[40:41], v[22:23]
	v_pk_fma_f32 v[30:31], v[8:9], v[32:33], v[30:31]
	v_pk_fma_f32 v[40:41], v[10:11], v[34:35], v[40:41]
	v_pk_fma_f32 v[30:31], v[12:13], v[38:39], v[30:31]
	v_pk_fma_f32 v[40:41], v[14:15], v[42:43], v[40:41]
	v_pk_fma_f32 v[30:31], v[4:5], v[28:29], v[30:31]
	v_pk_fma_f32 v[40:41], v[6:7], v[36:37], v[40:41]
	v_mul_f32_e32 v45, 0xbfb8aa3b, v31
	v_mul_f32_e32 v44, 0xbfb8aa3b, v30
	v_exp_f32_e32 v45, v45
	v_mul_f32_e32 v46, 0xbfb8aa3b, v40
	v_exp_f32_e32 v44, v44
	v_exp_f32_e32 v47, v46
	v_mul_f32_e32 v46, 0xbfb8aa3b, v41
	v_exp_f32_e32 v48, v46
	v_add_f32_e32 v45, 1.0, v45
	v_add_f32_e32 v44, 1.0, v44
	v_rcp_f32_e32 v46, v45
	v_add_f32_e32 v45, 1.0, v47
	v_rcp_f32_e32 v44, v44
	v_rcp_f32_e32 v45, v45
	v_add_f32_e32 v47, 1.0, v48
	v_rcp_f32_e32 v47, v47
	v_mov_b32_e32 v48, v30
	v_mov_b32_e32 v49, v40
	v_pk_mul_f32 v[44:45], v[48:49], v[44:45]
	v_mov_b32_e32 v40, v31
	v_pk_mul_f32 v[30:31], v[40:41], v[46:47]
	v_and_b32_sdwa v41, v44, v173 dst_sel:DWORD dst_unused:UNUSED_PAD src0_sel:WORD_1 src1_sel:DWORD
	v_and_b32_sdwa v40, v45, v173 dst_sel:DWORD dst_unused:UNUSED_PAD src0_sel:WORD_1 src1_sel:DWORD
	v_add3_u32 v41, v44, v41, s71
	v_and_b32_sdwa v44, v31, v173 dst_sel:DWORD dst_unused:UNUSED_PAD src0_sel:WORD_1 src1_sel:DWORD
	v_add3_u32 v40, v45, v40, s71
	v_and_b32_sdwa v45, v30, v173 dst_sel:DWORD dst_unused:UNUSED_PAD src0_sel:WORD_1 src1_sel:DWORD
	v_add3_u32 v31, v31, v44, s71
	v_add3_u32 v30, v30, v45, s71
	v_and_b32_e32 v31, 0xffff0000, v31
	v_and_b32_e32 v30, 0xffff0000, v30
	v_or_b32_sdwa v31, v31, v40 dst_sel:DWORD dst_unused:UNUSED_PAD src0_sel:DWORD src1_sel:WORD_1
	v_or_b32_e32 v40, 2, v50
	v_or_b32_sdwa v30, v30, v41 dst_sel:DWORD dst_unused:UNUSED_PAD src0_sel:DWORD src1_sel:WORD_1
	v_mad_i64_i32 v[40:41], s[6:7], v40, s3, v[26:27]
	global_store_dwordx2 v[40:41], v[30:31], off
	v_or_b32_e32 v30, 5, v51
	v_cmp_lt_u32_e32 vcc, v30, v53
	v_mov_b32_e32 v30, 0
	v_mov_b32_e32 v44, 0
	v_mov_b32_e32 v45, 0
	v_mov_b32_e32 v46, 0
	v_mov_b32_e32 v47, 0
	s_and_saveexec_b64 s[6:7], vcc
	s_cbranch_execz .LBB0_228
	s_waitcnt vmcnt(15)
	v_lshlrev_b32_e32 v44, 16, v66
	v_and_b32_e32 v45, 0xffff0000, v66
	v_lshlrev_b32_e32 v46, 16, v67
	v_and_b32_e32 v47, 0xffff0000, v67
.LBB0_228:
	s_or_b64 exec, exec, s[6:7]
	v_pk_fma_f32 v[32:33], v[16:17], v[32:33], v[20:21]
	v_pk_fma_f32 v[34:35], v[18:19], v[34:35], v[22:23]
	v_pk_fma_f32 v[32:33], v[8:9], v[38:39], v[32:33]
	v_pk_fma_f32 v[34:35], v[10:11], v[42:43], v[34:35]
	v_pk_fma_f32 v[32:33], v[12:13], v[28:29], v[32:33]
	v_pk_fma_f32 v[34:35], v[14:15], v[36:37], v[34:35]
	v_pk_fma_f32 v[32:33], v[4:5], v[44:45], v[32:33]
	v_pk_fma_f32 v[34:35], v[6:7], v[46:47], v[34:35]
	v_mul_f32_e32 v31, 0xbfb8aa3b, v32
	v_exp_f32_e32 v31, v31
	v_mul_f32_e32 v40, 0xbfb8aa3b, v33
	v_exp_f32_e32 v41, v40
	v_mul_f32_e32 v48, 0xbfb8aa3b, v35
	v_add_f32_e32 v31, 1.0, v31
	v_rcp_f32_e32 v40, v31
	v_add_f32_e32 v31, 1.0, v41
	v_mul_f32_e32 v41, 0xbfb8aa3b, v34
	v_exp_f32_e32 v41, v41
	v_exp_f32_e32 v49, v48
	v_rcp_f32_e32 v48, v31
	v_mov_b32_e32 v54, v32
	v_add_f32_e32 v31, 1.0, v41
	v_rcp_f32_e32 v41, v31
	v_add_f32_e32 v31, 1.0, v49
	v_rcp_f32_e32 v49, v31
	v_mov_b32_e32 v55, v34
	v_mov_b32_e32 v34, v33
	v_pk_mul_f32 v[40:41], v[54:55], v[40:41]
	v_pk_mul_f32 v[32:33], v[34:35], v[48:49]
	v_and_b32_sdwa v34, v40, v173 dst_sel:DWORD dst_unused:UNUSED_PAD src0_sel:WORD_1 src1_sel:DWORD
	v_and_b32_sdwa v35, v33, v173 dst_sel:DWORD dst_unused:UNUSED_PAD src0_sel:WORD_1 src1_sel:DWORD
	v_and_b32_sdwa v31, v41, v173 dst_sel:DWORD dst_unused:UNUSED_PAD src0_sel:WORD_1 src1_sel:DWORD
	v_add3_u32 v34, v40, v34, s71
	v_and_b32_sdwa v40, v32, v173 dst_sel:DWORD dst_unused:UNUSED_PAD src0_sel:WORD_1 src1_sel:DWORD
	v_add3_u32 v33, v33, v35, s71
	v_add3_u32 v31, v41, v31, s71
	v_add3_u32 v32, v32, v40, s71
	v_and_b32_e32 v33, 0xffff0000, v33
	v_and_b32_e32 v32, 0xffff0000, v32
	v_or_b32_sdwa v33, v33, v31 dst_sel:DWORD dst_unused:UNUSED_PAD src0_sel:DWORD src1_sel:WORD_1
	v_or_b32_e32 v31, 3, v50
	v_or_b32_sdwa v32, v32, v34 dst_sel:DWORD dst_unused:UNUSED_PAD src0_sel:DWORD src1_sel:WORD_1
	v_mad_i64_i32 v[34:35], s[6:7], v31, s3, v[26:27]
	v_or_b32_e32 v31, 6, v51
	v_cmp_lt_u32_e32 vcc, v31, v53
	v_mov_b32_e32 v31, 0
	v_mov_b32_e32 v40, 0
	v_mov_b32_e32 v41, 0
	global_store_dwordx2 v[34:35], v[32:33], off
	s_and_saveexec_b64 s[6:7], vcc
	s_cbranch_execz .LBB0_230
	s_waitcnt vmcnt(15)
	v_lshlrev_b32_e32 v30, 16, v68
	v_and_b32_e32 v31, 0xffff0000, v68
	v_lshlrev_b32_e32 v40, 16, v69
	v_and_b32_e32 v41, 0xffff0000, v69
; __device__ __forceinline__ float silu_(float x) { return x * sigmoid_(x); }
; __device__ __forceinline__ unsigned pk2(float lo, float hi) { return f2bf(lo) | (f2bf(hi) << 16); }
; __device__ __forceinline__ f32x4 ld_bf4(const bf16* p) { const u32x2 w = *(const u32x2*)p; return (f32x4){__builtin_bit_cast(float, w.x << 16), __builtin_bit_cast(float, w.x & 0xffff0000u), __builtin_bit_cast(float, w.y << 16), __builtin_bit_cast(float, w.y & 0xffff0000u)}; }
; __device__ __forceinline__ void prep_phase(const Params& P, float* L, int l) {
;     ...
;           f32x4 xm1 = (t0 > 0) ? ld_bf4(up - NUG) : z4, x0 = ld_bf4(up), x1 = ld_bf4(up + NUG);
; #pragma unroll
;           for (int r = 0; r < 16; ++r) {
;               const f32x4 x2 = (t0 + r + 2 < len) ? ld_bf4(up + (size_t)(r + 2) * NUG) : z4;
;               f32x4 v = bb + xm1 * w0 + x0 * w1 + x1 * w2 + x2 * w3;
;               v.x = silu_(v.x); v.y = silu_(v.y); v.z = silu_(v.z); v.w = silu_(v.w);
;               { u32x2 w_; w_.x = pk2(v.x, v.y); w_.y = pk2(v.z, v.w); *(u32x2*)(XBC + (size_t)(row0 + r) * 768 + c4) = w_; }
;               xm1 = x0; x0 = x1; x1 = x2;
.LBB0_230:
	s_or_b64 exec, exec, s[6:7]
	v_pk_fma_f32 v[34:35], v[16:17], v[38:39], v[20:21]
	v_pk_fma_f32 v[32:33], v[18:19], v[42:43], v[22:23]
	v_pk_fma_f32 v[34:35], v[8:9], v[28:29], v[34:35]
	v_pk_fma_f32 v[32:33], v[10:11], v[36:37], v[32:33]
	v_pk_fma_f32 v[34:35], v[12:13], v[44:45], v[34:35]
	v_pk_fma_f32 v[32:33], v[14:15], v[46:47], v[32:33]
	v_pk_fma_f32 v[34:35], v[4:5], v[30:31], v[34:35]
	v_pk_fma_f32 v[32:33], v[6:7], v[40:41], v[32:33]
	v_mul_f32_e32 v39, 0xbfb8aa3b, v35
	v_mul_f32_e32 v38, 0xbfb8aa3b, v34
	v_exp_f32_e32 v39, v39
	v_mul_f32_e32 v42, 0xbfb8aa3b, v32
	v_exp_f32_e32 v38, v38
	v_exp_f32_e32 v43, v42
	v_mul_f32_e32 v42, 0xbfb8aa3b, v33
	v_exp_f32_e32 v48, v42
	v_add_f32_e32 v39, 1.0, v39
	v_add_f32_e32 v38, 1.0, v38
	v_rcp_f32_e32 v42, v39
	v_add_f32_e32 v39, 1.0, v43
	v_rcp_f32_e32 v38, v38
	v_rcp_f32_e32 v39, v39
	v_add_f32_e32 v43, 1.0, v48
	v_rcp_f32_e32 v43, v43
	v_mov_b32_e32 v48, v34
	v_mov_b32_e32 v49, v32
	v_pk_mul_f32 v[38:39], v[48:49], v[38:39]
	v_mov_b32_e32 v32, v35
	v_pk_mul_f32 v[32:33], v[32:33], v[42:43]
	v_and_b32_sdwa v35, v38, v173 dst_sel:DWORD dst_unused:UNUSED_PAD src0_sel:WORD_1 src1_sel:DWORD
	v_and_b32_sdwa v34, v39, v173 dst_sel:DWORD dst_unused:UNUSED_PAD src0_sel:WORD_1 src1_sel:DWORD
	v_add3_u32 v35, v38, v35, s71
	v_and_b32_sdwa v38, v33, v173 dst_sel:DWORD dst_unused:UNUSED_PAD src0_sel:WORD_1 src1_sel:DWORD
	v_add3_u32 v34, v39, v34, s71
	v_and_b32_sdwa v39, v32, v173 dst_sel:DWORD dst_unused:UNUSED_PAD src0_sel:WORD_1 src1_sel:DWORD
	v_add3_u32 v33, v33, v38, s71
	v_add3_u32 v32, v32, v39, s71
	v_and_b32_e32 v33, 0xffff0000, v33
	v_and_b32_e32 v32, 0xffff0000, v32
	v_or_b32_sdwa v33, v33, v34 dst_sel:DWORD dst_unused:UNUSED_PAD src0_sel:DWORD src1_sel:WORD_1
	v_or_b32_e32 v34, 4, v50
	v_or_b32_sdwa v32, v32, v35 dst_sel:DWORD dst_unused:UNUSED_PAD src0_sel:DWORD src1_sel:WORD_1
	v_mad_i64_i32 v[34:35], s[6:7], v34, s3, v[26:27]
	global_store_dwordx2 v[34:35], v[32:33], off
	v_or_b32_e32 v32, 7, v51
	v_cmp_lt_u32_e32 vcc, v32, v53
	v_mov_b32_e32 v34, 0
	v_mov_b32_e32 v42, 0
	v_mov_b32_e32 v43, 0
	v_mov_b32_e32 v48, 0
	v_mov_b32_e32 v49, 0
	s_and_saveexec_b64 s[6:7], vcc
	s_cbranch_execz .LBB0_232
	s_waitcnt vmcnt(15)
	v_lshlrev_b32_e32 v42, 16, v70
	v_and_b32_e32 v43, 0xffff0000, v70
	v_lshlrev_b32_e32 v48, 16, v71
	v_and_b32_e32 v49, 0xffff0000, v71
.LBB0_232:
	s_or_b64 exec, exec, s[6:7]
	v_pk_fma_f32 v[28:29], v[16:17], v[28:29], v[20:21]
	v_pk_fma_f32 v[32:33], v[18:19], v[36:37], v[22:23]
	v_pk_fma_f32 v[28:29], v[8:9], v[44:45], v[28:29]
	v_pk_fma_f32 v[32:33], v[10:11], v[46:47], v[32:33]
	v_pk_fma_f32 v[28:29], v[12:13], v[30:31], v[28:29]
	v_pk_fma_f32 v[32:33], v[14:15], v[40:41], v[32:33]
	v_pk_fma_f32 v[28:29], v[4:5], v[42:43], v[28:29]
	v_pk_fma_f32 v[32:33], v[6:7], v[48:49], v[32:33]
	v_mul_f32_e32 v35, 0xbfb8aa3b, v28
	v_exp_f32_e32 v35, v35
	v_mul_f32_e32 v36, 0xbfb8aa3b, v29
	v_exp_f32_e32 v37, v36
	v_mul_f32_e32 v38, 0xbfb8aa3b, v33
	v_add_f32_e32 v35, 1.0, v35
	v_rcp_f32_e32 v36, v35
	v_add_f32_e32 v35, 1.0, v37
	v_mul_f32_e32 v37, 0xbfb8aa3b, v32
	v_exp_f32_e32 v37, v37
	v_exp_f32_e32 v39, v38
	v_rcp_f32_e32 v38, v35
	v_mov_b32_e32 v54, v28
	v_add_f32_e32 v35, 1.0, v37
	v_rcp_f32_e32 v37, v35
	v_add_f32_e32 v35, 1.0, v39
	v_rcp_f32_e32 v39, v35
	v_mov_b32_e32 v55, v32
	v_mov_b32_e32 v32, v29
	v_pk_mul_f32 v[36:37], v[54:55], v[36:37]
	v_pk_mul_f32 v[28:29], v[32:33], v[38:39]
	v_and_b32_sdwa v33, v36, v173 dst_sel:DWORD dst_unused:UNUSED_PAD src0_sel:WORD_1 src1_sel:DWORD
	v_and_b32_sdwa v35, v29, v173 dst_sel:DWORD dst_unused:UNUSED_PAD src0_sel:WORD_1 src1_sel:DWORD
	v_and_b32_sdwa v32, v37, v173 dst_sel:DWORD dst_unused:UNUSED_PAD src0_sel:WORD_1 src1_sel:DWORD
	v_add3_u32 v33, v36, v33, s71
	v_and_b32_sdwa v36, v28, v173 dst_sel:DWORD dst_unused:UNUSED_PAD src0_sel:WORD_1 src1_sel:DWORD
	v_add3_u32 v29, v29, v35, s71
	v_add3_u32 v32, v37, v32, s71
	v_add3_u32 v28, v28, v36, s71
	v_and_b32_e32 v29, 0xffff0000, v29
	v_and_b32_e32 v28, 0xffff0000, v28
	v_or_b32_sdwa v29, v29, v32 dst_sel:DWORD dst_unused:UNUSED_PAD src0_sel:DWORD src1_sel:WORD_1
	v_or_b32_e32 v32, 5, v50
	v_or_b32_sdwa v28, v28, v33 dst_sel:DWORD dst_unused:UNUSED_PAD src0_sel:DWORD src1_sel:WORD_1
	v_mad_i64_i32 v[32:33], s[6:7], v32, s3, v[26:27]
	global_store_dwordx2 v[32:33], v[28:29], off
	v_or_b32_e32 v28, 8, v51
	v_cmp_lt_u32_e32 vcc, v28, v53
	v_mov_b32_e32 v35, 0
	v_mov_b32_e32 v28, 0
	v_mov_b32_e32 v29, 0
	s_and_saveexec_b64 s[6:7], vcc
	s_cbranch_execz .LBB0_234
	s_waitcnt vmcnt(15)
	v_lshlrev_b32_e32 v34, 16, v72
	v_and_b32_e32 v35, 0xffff0000, v72
	v_lshlrev_b32_e32 v28, 16, v73
	v_and_b32_e32 v29, 0xffff0000, v73
; __device__ __forceinline__ float silu_(float x) { return x * sigmoid_(x); }
; __device__ __forceinline__ unsigned pk2(float lo, float hi) { return f2bf(lo) | (f2bf(hi) << 16); }
; __device__ __forceinline__ f32x4 ld_bf4(const bf16* p) { const u32x2 w = *(const u32x2*)p; return (f32x4){__builtin_bit_cast(float, w.x << 16), __builtin_bit_cast(float, w.x & 0xffff0000u), __builtin_bit_cast(float, w.y << 16), __builtin_bit_cast(float, w.y & 0xffff0000u)}; }
; __device__ __forceinline__ void prep_phase(const Params& P, float* L, int l) {
;     ...
;           f32x4 xm1 = (t0 > 0) ? ld_bf4(up - NUG) : z4, x0 = ld_bf4(up), x1 = ld_bf4(up + NUG);
; #pragma unroll
;           for (int r = 0; r < 16; ++r) {
;               const f32x4 x2 = (t0 + r + 2 < len) ? ld_bf4(up + (size_t)(r + 2) * NUG) : z4;
;               f32x4 v = bb + xm1 * w0 + x0 * w1 + x1 * w2 + x2 * w3;
;               v.x = silu_(v.x); v.y = silu_(v.y); v.z = silu_(v.z); v.w = silu_(v.w);
;               { u32x2 w_; w_.x = pk2(v.x, v.y); w_.y = pk2(v.z, v.w); *(u32x2*)(XBC + (size_t)(row0 + r) * 768 + c4) = w_; }
;               xm1 = x0; x0 = x1; x1 = x2;
.LBB0_234:
	s_or_b64 exec, exec, s[6:7]
	v_pk_fma_f32 v[36:37], v[16:17], v[44:45], v[20:21]
	v_pk_fma_f32 v[32:33], v[18:19], v[46:47], v[22:23]
	v_pk_fma_f32 v[36:37], v[8:9], v[30:31], v[36:37]
	v_pk_fma_f32 v[32:33], v[10:11], v[40:41], v[32:33]
	v_pk_fma_f32 v[36:37], v[12:13], v[42:43], v[36:37]
	v_pk_fma_f32 v[32:33], v[14:15], v[48:49], v[32:33]
	v_pk_fma_f32 v[36:37], v[4:5], v[34:35], v[36:37]
	v_pk_fma_f32 v[32:33], v[6:7], v[28:29], v[32:33]
	v_mul_f32_e32 v39, 0xbfb8aa3b, v37
	v_mul_f32_e32 v38, 0xbfb8aa3b, v36
	v_exp_f32_e32 v39, v39
	v_mul_f32_e32 v44, 0xbfb8aa3b, v32
	v_exp_f32_e32 v38, v38
	v_exp_f32_e32 v45, v44
	v_mul_f32_e32 v44, 0xbfb8aa3b, v33
	v_exp_f32_e32 v46, v44
	v_add_f32_e32 v39, 1.0, v39
	v_add_f32_e32 v38, 1.0, v38
	v_rcp_f32_e32 v44, v39
	v_add_f32_e32 v39, 1.0, v45
	v_rcp_f32_e32 v38, v38
	v_rcp_f32_e32 v39, v39
	v_add_f32_e32 v45, 1.0, v46
	v_rcp_f32_e32 v45, v45
	v_mov_b32_e32 v46, v36
	v_mov_b32_e32 v47, v32
	v_pk_mul_f32 v[38:39], v[46:47], v[38:39]
	v_mov_b32_e32 v32, v37
	v_pk_mul_f32 v[32:33], v[32:33], v[44:45]
	v_and_b32_sdwa v37, v38, v173 dst_sel:DWORD dst_unused:UNUSED_PAD src0_sel:WORD_1 src1_sel:DWORD
	v_and_b32_sdwa v36, v39, v173 dst_sel:DWORD dst_unused:UNUSED_PAD src0_sel:WORD_1 src1_sel:DWORD
	v_add3_u32 v37, v38, v37, s71
	v_and_b32_sdwa v38, v33, v173 dst_sel:DWORD dst_unused:UNUSED_PAD src0_sel:WORD_1 src1_sel:DWORD
	v_add3_u32 v36, v39, v36, s71
	v_and_b32_sdwa v39, v32, v173 dst_sel:DWORD dst_unused:UNUSED_PAD src0_sel:WORD_1 src1_sel:DWORD
	v_add3_u32 v33, v33, v38, s71
	v_add3_u32 v32, v32, v39, s71
	v_and_b32_e32 v33, 0xffff0000, v33
	v_and_b32_e32 v32, 0xffff0000, v32
	v_or_b32_sdwa v33, v33, v36 dst_sel:DWORD dst_unused:UNUSED_PAD src0_sel:DWORD src1_sel:WORD_1
	v_or_b32_e32 v36, 6, v50
	v_or_b32_sdwa v32, v32, v37 dst_sel:DWORD dst_unused:UNUSED_PAD src0_sel:DWORD src1_sel:WORD_1
	v_mad_i64_i32 v[36:37], s[6:7], v36, s3, v[26:27]
	global_store_dwordx2 v[36:37], v[32:33], off
	v_or_b32_e32 v32, 9, v51
	v_cmp_lt_u32_e32 vcc, v32, v53
	v_mov_b32_e32 v32, 0
	v_mov_b32_e32 v38, 0
	v_mov_b32_e32 v39, 0
	v_mov_b32_e32 v46, 0
	v_mov_b32_e32 v47, 0
	s_and_saveexec_b64 s[6:7], vcc
	s_cbranch_execz .LBB0_236
	s_waitcnt vmcnt(15)
	v_lshlrev_b32_e32 v38, 16, v74
	v_and_b32_e32 v39, 0xffff0000, v74
	v_lshlrev_b32_e32 v46, 16, v75
	v_and_b32_e32 v47, 0xffff0000, v75
.LBB0_236:
	s_or_b64 exec, exec, s[6:7]
	v_pk_fma_f32 v[30:31], v[16:17], v[30:31], v[20:21]
	v_pk_fma_f32 v[36:37], v[18:19], v[40:41], v[22:23]
	v_pk_fma_f32 v[30:31], v[8:9], v[42:43], v[30:31]
	v_pk_fma_f32 v[36:37], v[10:11], v[48:49], v[36:37]
	v_pk_fma_f32 v[30:31], v[12:13], v[34:35], v[30:31]
	v_pk_fma_f32 v[36:37], v[14:15], v[28:29], v[36:37]
	v_pk_fma_f32 v[30:31], v[4:5], v[38:39], v[30:31]
	v_pk_fma_f32 v[36:37], v[6:7], v[46:47], v[36:37]
	v_mul_f32_e32 v33, 0xbfb8aa3b, v30
	v_exp_f32_e32 v33, v33
	v_mul_f32_e32 v40, 0xbfb8aa3b, v31
	v_exp_f32_e32 v41, v40
	v_mul_f32_e32 v44, 0xbfb8aa3b, v37
	v_add_f32_e32 v33, 1.0, v33
	v_rcp_f32_e32 v40, v33
	v_add_f32_e32 v33, 1.0, v41
	v_mul_f32_e32 v41, 0xbfb8aa3b, v36
	v_exp_f32_e32 v41, v41
	v_exp_f32_e32 v45, v44
	v_rcp_f32_e32 v44, v33
	v_mov_b32_e32 v54, v30
	v_add_f32_e32 v33, 1.0, v41
	v_rcp_f32_e32 v41, v33
	v_add_f32_e32 v33, 1.0, v45
	v_rcp_f32_e32 v45, v33
	v_mov_b32_e32 v55, v36
	v_mov_b32_e32 v36, v31
	v_pk_mul_f32 v[40:41], v[54:55], v[40:41]
	v_pk_mul_f32 v[30:31], v[36:37], v[44:45]
	v_and_b32_sdwa v36, v40, v173 dst_sel:DWORD dst_unused:UNUSED_PAD src0_sel:WORD_1 src1_sel:DWORD
	v_and_b32_sdwa v37, v31, v173 dst_sel:DWORD dst_unused:UNUSED_PAD src0_sel:WORD_1 src1_sel:DWORD
	v_and_b32_sdwa v33, v41, v173 dst_sel:DWORD dst_unused:UNUSED_PAD src0_sel:WORD_1 src1_sel:DWORD
	v_add3_u32 v36, v40, v36, s71
	v_and_b32_sdwa v40, v30, v173 dst_sel:DWORD dst_unused:UNUSED_PAD src0_sel:WORD_1 src1_sel:DWORD
	v_add3_u32 v31, v31, v37, s71
	v_add3_u32 v33, v41, v33, s71
	v_add3_u32 v30, v30, v40, s71
	v_and_b32_e32 v31, 0xffff0000, v31
	v_and_b32_e32 v30, 0xffff0000, v30
	v_or_b32_sdwa v31, v31, v33 dst_sel:DWORD dst_unused:UNUSED_PAD src0_sel:DWORD src1_sel:WORD_1
	v_or_b32_e32 v33, 7, v50
	v_or_b32_sdwa v30, v30, v36 dst_sel:DWORD dst_unused:UNUSED_PAD src0_sel:DWORD src1_sel:WORD_1
	v_mad_i64_i32 v[36:37], s[6:7], v33, s3, v[26:27]
	global_store_dwordx2 v[36:37], v[30:31], off
	v_or_b32_e32 v30, 10, v51
	v_cmp_lt_u32_e32 vcc, v30, v53
	v_mov_b32_e32 v33, 0
	v_mov_b32_e32 v36, 0
	v_mov_b32_e32 v37, 0
	s_and_saveexec_b64 s[6:7], vcc
	s_cbranch_execz .LBB0_238
	s_waitcnt vmcnt(15)
	v_lshlrev_b32_e32 v32, 16, v76
	v_and_b32_e32 v33, 0xffff0000, v76
	v_lshlrev_b32_e32 v36, 16, v77
	v_and_b32_e32 v37, 0xffff0000, v77
; __device__ __forceinline__ float silu_(float x) { return x * sigmoid_(x); }
; __device__ __forceinline__ unsigned pk2(float lo, float hi) { return f2bf(lo) | (f2bf(hi) << 16); }
; __device__ __forceinline__ f32x4 ld_bf4(const bf16* p) { const u32x2 w = *(const u32x2*)p; return (f32x4){__builtin_bit_cast(float, w.x << 16), __builtin_bit_cast(float, w.x & 0xffff0000u), __builtin_bit_cast(float, w.y << 16), __builtin_bit_cast(float, w.y & 0xffff0000u)}; }
; __device__ __forceinline__ void prep_phase(const Params& P, float* L, int l) {
;     ...
;           f32x4 xm1 = (t0 > 0) ? ld_bf4(up - NUG) : z4, x0 = ld_bf4(up), x1 = ld_bf4(up + NUG);
; #pragma unroll
;           for (int r = 0; r < 16; ++r) {
;               const f32x4 x2 = (t0 + r + 2 < len) ? ld_bf4(up + (size_t)(r + 2) * NUG) : z4;
;               f32x4 v = bb + xm1 * w0 + x0 * w1 + x1 * w2 + x2 * w3;
;               v.x = silu_(v.x); v.y = silu_(v.y); v.z = silu_(v.z); v.w = silu_(v.w);
;               { u32x2 w_; w_.x = pk2(v.x, v.y); w_.y = pk2(v.z, v.w); *(u32x2*)(XBC + (size_t)(row0 + r) * 768 + c4) = w_; }
;               xm1 = x0; x0 = x1; x1 = x2;
.LBB0_238:
	s_or_b64 exec, exec, s[6:7]
	v_pk_fma_f32 v[40:41], v[16:17], v[42:43], v[20:21]
	v_pk_fma_f32 v[30:31], v[18:19], v[48:49], v[22:23]
	v_pk_fma_f32 v[40:41], v[8:9], v[34:35], v[40:41]
	v_pk_fma_f32 v[30:31], v[10:11], v[28:29], v[30:31]
	v_pk_fma_f32 v[40:41], v[12:13], v[38:39], v[40:41]
	v_pk_fma_f32 v[30:31], v[14:15], v[46:47], v[30:31]
	v_pk_fma_f32 v[40:41], v[4:5], v[32:33], v[40:41]
	v_pk_fma_f32 v[30:31], v[6:7], v[36:37], v[30:31]
	v_mul_f32_e32 v43, 0xbfb8aa3b, v41
	v_mul_f32_e32 v42, 0xbfb8aa3b, v40
	v_exp_f32_e32 v43, v43
	v_mul_f32_e32 v44, 0xbfb8aa3b, v30
	v_exp_f32_e32 v42, v42
	v_exp_f32_e32 v45, v44
	v_mul_f32_e32 v44, 0xbfb8aa3b, v31
	v_exp_f32_e32 v48, v44
	v_add_f32_e32 v43, 1.0, v43
	v_add_f32_e32 v42, 1.0, v42
	v_rcp_f32_e32 v44, v43
	v_add_f32_e32 v43, 1.0, v45
	v_rcp_f32_e32 v42, v42
	v_rcp_f32_e32 v43, v43
	v_add_f32_e32 v45, 1.0, v48
	v_rcp_f32_e32 v45, v45
	v_mov_b32_e32 v48, v40
	v_mov_b32_e32 v49, v30
	v_pk_mul_f32 v[42:43], v[48:49], v[42:43]
	v_mov_b32_e32 v30, v41
	v_pk_mul_f32 v[30:31], v[30:31], v[44:45]
	v_and_b32_sdwa v41, v42, v173 dst_sel:DWORD dst_unused:UNUSED_PAD src0_sel:WORD_1 src1_sel:DWORD
	v_and_b32_sdwa v40, v43, v173 dst_sel:DWORD dst_unused:UNUSED_PAD src0_sel:WORD_1 src1_sel:DWORD
	v_add3_u32 v41, v42, v41, s71
	v_and_b32_sdwa v42, v31, v173 dst_sel:DWORD dst_unused:UNUSED_PAD src0_sel:WORD_1 src1_sel:DWORD
	v_add3_u32 v40, v43, v40, s71
	v_and_b32_sdwa v43, v30, v173 dst_sel:DWORD dst_unused:UNUSED_PAD src0_sel:WORD_1 src1_sel:DWORD
	v_add3_u32 v31, v31, v42, s71
	v_add3_u32 v30, v30, v43, s71
	v_and_b32_e32 v31, 0xffff0000, v31
	v_and_b32_e32 v30, 0xffff0000, v30
	v_or_b32_sdwa v31, v31, v40 dst_sel:DWORD dst_unused:UNUSED_PAD src0_sel:DWORD src1_sel:WORD_1
	v_or_b32_e32 v40, 8, v50
	v_or_b32_sdwa v30, v30, v41 dst_sel:DWORD dst_unused:UNUSED_PAD src0_sel:DWORD src1_sel:WORD_1
	v_mad_i64_i32 v[40:41], s[6:7], v40, s3, v[26:27]
	global_store_dwordx2 v[40:41], v[30:31], off
	v_or_b32_e32 v30, 11, v51
	v_cmp_lt_u32_e32 vcc, v30, v53
	v_mov_b32_e32 v30, 0
	v_mov_b32_e32 v40, 0
	v_mov_b32_e32 v41, 0
	v_mov_b32_e32 v44, 0
	v_mov_b32_e32 v45, 0
	s_and_saveexec_b64 s[6:7], vcc
	s_cbranch_execz .LBB0_240
	s_waitcnt vmcnt(15)
	v_lshlrev_b32_e32 v40, 16, v78
	v_and_b32_e32 v41, 0xffff0000, v78
	v_lshlrev_b32_e32 v44, 16, v79
	v_and_b32_e32 v45, 0xffff0000, v79
.LBB0_240:
	s_or_b64 exec, exec, s[6:7]
	v_pk_fma_f32 v[34:35], v[16:17], v[34:35], v[20:21]
	v_pk_fma_f32 v[28:29], v[18:19], v[28:29], v[22:23]
	v_pk_fma_f32 v[34:35], v[8:9], v[38:39], v[34:35]
	v_pk_fma_f32 v[28:29], v[10:11], v[46:47], v[28:29]
	v_pk_fma_f32 v[34:35], v[12:13], v[32:33], v[34:35]
	v_pk_fma_f32 v[28:29], v[14:15], v[36:37], v[28:29]
	v_pk_fma_f32 v[34:35], v[4:5], v[40:41], v[34:35]
	v_pk_fma_f32 v[28:29], v[6:7], v[44:45], v[28:29]
	v_mul_f32_e32 v31, 0xbfb8aa3b, v34
	v_exp_f32_e32 v31, v31
	v_mul_f32_e32 v42, 0xbfb8aa3b, v35
	v_exp_f32_e32 v43, v42
	v_mul_f32_e32 v48, 0xbfb8aa3b, v29
	v_add_f32_e32 v31, 1.0, v31
	v_rcp_f32_e32 v42, v31
	v_add_f32_e32 v31, 1.0, v43
	v_mul_f32_e32 v43, 0xbfb8aa3b, v28
	v_exp_f32_e32 v43, v43
	v_exp_f32_e32 v49, v48
	v_rcp_f32_e32 v48, v31
	v_mov_b32_e32 v54, v34
	v_add_f32_e32 v31, 1.0, v43
	v_rcp_f32_e32 v43, v31
	v_add_f32_e32 v31, 1.0, v49
	v_rcp_f32_e32 v49, v31
	v_mov_b32_e32 v55, v28
	v_mov_b32_e32 v28, v35
	v_pk_mul_f32 v[42:43], v[54:55], v[42:43]
	v_pk_mul_f32 v[28:29], v[28:29], v[48:49]
	v_and_b32_sdwa v34, v42, v173 dst_sel:DWORD dst_unused:UNUSED_PAD src0_sel:WORD_1 src1_sel:DWORD
	v_and_b32_sdwa v35, v29, v173 dst_sel:DWORD dst_unused:UNUSED_PAD src0_sel:WORD_1 src1_sel:DWORD
	v_and_b32_sdwa v31, v43, v173 dst_sel:DWORD dst_unused:UNUSED_PAD src0_sel:WORD_1 src1_sel:DWORD
	v_add3_u32 v34, v42, v34, s71
	v_and_b32_sdwa v42, v28, v173 dst_sel:DWORD dst_unused:UNUSED_PAD src0_sel:WORD_1 src1_sel:DWORD
	v_add3_u32 v29, v29, v35, s71
	v_add3_u32 v31, v43, v31, s71
	v_add3_u32 v28, v28, v42, s71
	v_and_b32_e32 v29, 0xffff0000, v29
	v_and_b32_e32 v28, 0xffff0000, v28
	v_or_b32_sdwa v29, v29, v31 dst_sel:DWORD dst_unused:UNUSED_PAD src0_sel:DWORD src1_sel:WORD_1
	v_or_b32_e32 v31, 9, v50
	v_or_b32_sdwa v28, v28, v34 dst_sel:DWORD dst_unused:UNUSED_PAD src0_sel:DWORD src1_sel:WORD_1
	v_mad_i64_i32 v[34:35], s[6:7], v31, s3, v[26:27]
	global_store_dwordx2 v[34:35], v[28:29], off
	v_or_b32_e32 v28, 12, v51
	v_cmp_lt_u32_e32 vcc, v28, v53
	v_mov_b32_e32 v31, 0
	v_mov_b32_e32 v34, 0
	v_mov_b32_e32 v35, 0
	s_and_saveexec_b64 s[6:7], vcc
	s_cbranch_execz .LBB0_242
	s_waitcnt vmcnt(15)
	v_lshlrev_b32_e32 v30, 16, v80
	v_and_b32_e32 v31, 0xffff0000, v80
	v_lshlrev_b32_e32 v34, 16, v81
	v_and_b32_e32 v35, 0xffff0000, v81
; __device__ __forceinline__ float silu_(float x) { return x * sigmoid_(x); }
; __device__ __forceinline__ unsigned pk2(float lo, float hi) { return f2bf(lo) | (f2bf(hi) << 16); }
; __device__ __forceinline__ f32x4 ld_bf4(const bf16* p) { const u32x2 w = *(const u32x2*)p; return (f32x4){__builtin_bit_cast(float, w.x << 16), __builtin_bit_cast(float, w.x & 0xffff0000u), __builtin_bit_cast(float, w.y << 16), __builtin_bit_cast(float, w.y & 0xffff0000u)}; }
; __device__ __forceinline__ void prep_phase(const Params& P, float* L, int l) {
;     ...
;           f32x4 xm1 = (t0 > 0) ? ld_bf4(up - NUG) : z4, x0 = ld_bf4(up), x1 = ld_bf4(up + NUG);
; #pragma unroll
;           for (int r = 0; r < 16; ++r) {
;               const f32x4 x2 = (t0 + r + 2 < len) ? ld_bf4(up + (size_t)(r + 2) * NUG) : z4;
;               f32x4 v = bb + xm1 * w0 + x0 * w1 + x1 * w2 + x2 * w3;
;               v.x = silu_(v.x); v.y = silu_(v.y); v.z = silu_(v.z); v.w = silu_(v.w);
;               { u32x2 w_; w_.x = pk2(v.x, v.y); w_.y = pk2(v.z, v.w); *(u32x2*)(XBC + (size_t)(row0 + r) * 768 + c4) = w_; }
;               xm1 = x0; x0 = x1; x1 = x2;
.LBB0_242:
	s_or_b64 exec, exec, s[6:7]
	v_pk_fma_f32 v[38:39], v[16:17], v[38:39], v[20:21]
	v_pk_fma_f32 v[28:29], v[18:19], v[46:47], v[22:23]
	v_pk_fma_f32 v[38:39], v[8:9], v[32:33], v[38:39]
	v_pk_fma_f32 v[28:29], v[10:11], v[36:37], v[28:29]
	v_pk_fma_f32 v[38:39], v[12:13], v[40:41], v[38:39]
	v_pk_fma_f32 v[28:29], v[14:15], v[44:45], v[28:29]
	v_pk_fma_f32 v[38:39], v[4:5], v[30:31], v[38:39]
	v_pk_fma_f32 v[28:29], v[6:7], v[34:35], v[28:29]
	v_mul_f32_e32 v43, 0xbfb8aa3b, v39
	v_mul_f32_e32 v42, 0xbfb8aa3b, v38
	v_exp_f32_e32 v43, v43
	v_mul_f32_e32 v46, 0xbfb8aa3b, v28
	v_exp_f32_e32 v42, v42
	v_exp_f32_e32 v47, v46
	v_mul_f32_e32 v46, 0xbfb8aa3b, v29
	v_exp_f32_e32 v48, v46
	v_add_f32_e32 v43, 1.0, v43
	v_add_f32_e32 v42, 1.0, v42
	v_rcp_f32_e32 v46, v43
	v_add_f32_e32 v43, 1.0, v47
	v_rcp_f32_e32 v42, v42
	v_rcp_f32_e32 v43, v43
	v_add_f32_e32 v47, 1.0, v48
	v_rcp_f32_e32 v47, v47
	v_mov_b32_e32 v48, v38
	v_mov_b32_e32 v49, v28
	v_pk_mul_f32 v[42:43], v[48:49], v[42:43]
	v_mov_b32_e32 v28, v39
	v_pk_mul_f32 v[28:29], v[28:29], v[46:47]
	v_and_b32_sdwa v39, v42, v173 dst_sel:DWORD dst_unused:UNUSED_PAD src0_sel:WORD_1 src1_sel:DWORD
	v_and_b32_sdwa v38, v43, v173 dst_sel:DWORD dst_unused:UNUSED_PAD src0_sel:WORD_1 src1_sel:DWORD
	v_add3_u32 v39, v42, v39, s71
	v_and_b32_sdwa v42, v29, v173 dst_sel:DWORD dst_unused:UNUSED_PAD src0_sel:WORD_1 src1_sel:DWORD
	v_add3_u32 v38, v43, v38, s71
	v_and_b32_sdwa v43, v28, v173 dst_sel:DWORD dst_unused:UNUSED_PAD src0_sel:WORD_1 src1_sel:DWORD
	v_add3_u32 v29, v29, v42, s71
	v_add3_u32 v28, v28, v43, s71
	v_and_b32_e32 v29, 0xffff0000, v29
	v_and_b32_e32 v28, 0xffff0000, v28
	v_or_b32_sdwa v29, v29, v38 dst_sel:DWORD dst_unused:UNUSED_PAD src0_sel:DWORD src1_sel:WORD_1
	v_or_b32_e32 v38, 10, v50
	v_or_b32_sdwa v28, v28, v39 dst_sel:DWORD dst_unused:UNUSED_PAD src0_sel:DWORD src1_sel:WORD_1
	v_mad_i64_i32 v[38:39], s[6:7], v38, s3, v[26:27]
	global_store_dwordx2 v[38:39], v[28:29], off
	v_or_b32_e32 v28, 13, v51
	v_cmp_lt_u32_e32 vcc, v28, v53
	v_mov_b32_e32 v28, 0
	v_mov_b32_e32 v38, 0
	v_mov_b32_e32 v39, 0
	v_mov_b32_e32 v42, 0
	v_mov_b32_e32 v43, 0
	s_and_saveexec_b64 s[6:7], vcc
	s_cbranch_execz .LBB0_244
	s_waitcnt vmcnt(15)
	v_lshlrev_b32_e32 v38, 16, v82
	v_and_b32_e32 v39, 0xffff0000, v82
	v_lshlrev_b32_e32 v42, 16, v83
	v_and_b32_e32 v43, 0xffff0000, v83
.LBB0_244:
	s_or_b64 exec, exec, s[6:7]
	v_pk_fma_f32 v[32:33], v[16:17], v[32:33], v[20:21]
	v_pk_fma_f32 v[36:37], v[18:19], v[36:37], v[22:23]
	v_pk_fma_f32 v[32:33], v[8:9], v[40:41], v[32:33]
	v_pk_fma_f32 v[36:37], v[10:11], v[44:45], v[36:37]
	v_pk_fma_f32 v[32:33], v[12:13], v[30:31], v[32:33]
	v_pk_fma_f32 v[36:37], v[14:15], v[34:35], v[36:37]
	v_pk_fma_f32 v[32:33], v[4:5], v[38:39], v[32:33]
	v_pk_fma_f32 v[36:37], v[6:7], v[42:43], v[36:37]
	v_mul_f32_e32 v29, 0xbfb8aa3b, v32
	v_exp_f32_e32 v29, v29
	v_mul_f32_e32 v46, 0xbfb8aa3b, v33
	v_exp_f32_e32 v47, v46
	v_mul_f32_e32 v48, 0xbfb8aa3b, v37
	v_add_f32_e32 v29, 1.0, v29
	v_rcp_f32_e32 v46, v29
	v_add_f32_e32 v29, 1.0, v47
	v_mul_f32_e32 v47, 0xbfb8aa3b, v36
	v_exp_f32_e32 v47, v47
	v_exp_f32_e32 v49, v48
	v_rcp_f32_e32 v48, v29
	v_mov_b32_e32 v54, v32
	v_add_f32_e32 v29, 1.0, v47
	v_rcp_f32_e32 v47, v29
	v_add_f32_e32 v29, 1.0, v49
	v_rcp_f32_e32 v49, v29
	v_mov_b32_e32 v55, v36
	v_mov_b32_e32 v36, v33
	v_pk_mul_f32 v[46:47], v[54:55], v[46:47]
	v_pk_mul_f32 v[32:33], v[36:37], v[48:49]
	v_and_b32_sdwa v36, v46, v173 dst_sel:DWORD dst_unused:UNUSED_PAD src0_sel:WORD_1 src1_sel:DWORD
	v_and_b32_sdwa v37, v33, v173 dst_sel:DWORD dst_unused:UNUSED_PAD src0_sel:WORD_1 src1_sel:DWORD
	v_and_b32_sdwa v29, v47, v173 dst_sel:DWORD dst_unused:UNUSED_PAD src0_sel:WORD_1 src1_sel:DWORD
	v_add3_u32 v36, v46, v36, s71
	v_and_b32_sdwa v46, v32, v173 dst_sel:DWORD dst_unused:UNUSED_PAD src0_sel:WORD_1 src1_sel:DWORD
	v_add3_u32 v33, v33, v37, s71
	v_add3_u32 v29, v47, v29, s71
	v_add3_u32 v32, v32, v46, s71
	v_and_b32_e32 v33, 0xffff0000, v33
	v_and_b32_e32 v32, 0xffff0000, v32
	v_or_b32_sdwa v33, v33, v29 dst_sel:DWORD dst_unused:UNUSED_PAD src0_sel:DWORD src1_sel:WORD_1
	v_or_b32_e32 v29, 11, v50
	v_or_b32_sdwa v32, v32, v36 dst_sel:DWORD dst_unused:UNUSED_PAD src0_sel:DWORD src1_sel:WORD_1
	v_mad_i64_i32 v[36:37], s[6:7], v29, s3, v[26:27]
	v_or_b32_e32 v29, 14, v51
	global_store_dwordx2 v[36:37], v[32:33], off
	v_cmp_lt_u32_e32 vcc, v29, v53
	v_mov_b32_e32 v29, 0
	v_mov_b32_e32 v32, 0
	v_mov_b32_e32 v33, 0
	s_and_saveexec_b64 s[6:7], vcc
	s_cbranch_execz .LBB0_246
	s_waitcnt vmcnt(15)
	v_lshlrev_b32_e32 v28, 16, v84
	v_and_b32_e32 v29, 0xffff0000, v84
	v_lshlrev_b32_e32 v32, 16, v85
	v_and_b32_e32 v33, 0xffff0000, v85
; __device__ __forceinline__ float silu_(float x) { return x * sigmoid_(x); }
; __device__ __forceinline__ unsigned pk2(float lo, float hi) { return f2bf(lo) | (f2bf(hi) << 16); }
; __device__ __forceinline__ f32x4 ld_bf4(const bf16* p) { const u32x2 w = *(const u32x2*)p; return (f32x4){__builtin_bit_cast(float, w.x << 16), __builtin_bit_cast(float, w.x & 0xffff0000u), __builtin_bit_cast(float, w.y << 16), __builtin_bit_cast(float, w.y & 0xffff0000u)}; }
; __device__ __forceinline__ void prep_phase(const Params& P, float* L, int l) {
;     ...
;           f32x4 xm1 = (t0 > 0) ? ld_bf4(up - NUG) : z4, x0 = ld_bf4(up), x1 = ld_bf4(up + NUG);
; #pragma unroll
;           for (int r = 0; r < 16; ++r) {
;               const f32x4 x2 = (t0 + r + 2 < len) ? ld_bf4(up + (size_t)(r + 2) * NUG) : z4;
;               f32x4 v = bb + xm1 * w0 + x0 * w1 + x1 * w2 + x2 * w3;
;               v.x = silu_(v.x); v.y = silu_(v.y); v.z = silu_(v.z); v.w = silu_(v.w);
;               { u32x2 w_; w_.x = pk2(v.x, v.y); w_.y = pk2(v.z, v.w); *(u32x2*)(XBC + (size_t)(row0 + r) * 768 + c4) = w_; }
;               xm1 = x0; x0 = x1; x1 = x2;
.LBB0_246:
	s_or_b64 exec, exec, s[6:7]
	v_pk_fma_f32 v[40:41], v[16:17], v[40:41], v[20:21]
	v_pk_fma_f32 v[36:37], v[18:19], v[44:45], v[22:23]
	v_pk_fma_f32 v[40:41], v[8:9], v[30:31], v[40:41]
	v_pk_fma_f32 v[36:37], v[10:11], v[34:35], v[36:37]
	v_pk_fma_f32 v[40:41], v[12:13], v[38:39], v[40:41]
	v_pk_fma_f32 v[36:37], v[14:15], v[42:43], v[36:37]
	v_pk_fma_f32 v[40:41], v[4:5], v[28:29], v[40:41]
	v_pk_fma_f32 v[36:37], v[6:7], v[32:33], v[36:37]
	v_mul_f32_e32 v45, 0xbfb8aa3b, v41
	v_mul_f32_e32 v44, 0xbfb8aa3b, v40
	v_exp_f32_e32 v45, v45
	v_mul_f32_e32 v46, 0xbfb8aa3b, v36
	v_exp_f32_e32 v44, v44
	v_exp_f32_e32 v47, v46
	v_mul_f32_e32 v46, 0xbfb8aa3b, v37
	v_exp_f32_e32 v48, v46
	v_add_f32_e32 v45, 1.0, v45
	v_add_f32_e32 v44, 1.0, v44
	v_rcp_f32_e32 v46, v45
	v_add_f32_e32 v45, 1.0, v47
	v_rcp_f32_e32 v44, v44
	v_rcp_f32_e32 v45, v45
	v_add_f32_e32 v47, 1.0, v48
	v_rcp_f32_e32 v47, v47
	v_mov_b32_e32 v48, v40
	v_mov_b32_e32 v49, v36
	v_pk_mul_f32 v[44:45], v[48:49], v[44:45]
	v_mov_b32_e32 v36, v41
	v_pk_mul_f32 v[36:37], v[36:37], v[46:47]
	v_and_b32_sdwa v41, v44, v173 dst_sel:DWORD dst_unused:UNUSED_PAD src0_sel:WORD_1 src1_sel:DWORD
	v_and_b32_sdwa v40, v45, v173 dst_sel:DWORD dst_unused:UNUSED_PAD src0_sel:WORD_1 src1_sel:DWORD
	v_add3_u32 v41, v44, v41, s71
	v_and_b32_sdwa v44, v37, v173 dst_sel:DWORD dst_unused:UNUSED_PAD src0_sel:WORD_1 src1_sel:DWORD
	v_add3_u32 v40, v45, v40, s71
	v_and_b32_sdwa v45, v36, v173 dst_sel:DWORD dst_unused:UNUSED_PAD src0_sel:WORD_1 src1_sel:DWORD
	v_add3_u32 v37, v37, v44, s71
	v_add3_u32 v36, v36, v45, s71
	v_and_b32_e32 v37, 0xffff0000, v37
	v_and_b32_e32 v36, 0xffff0000, v36
	v_or_b32_sdwa v37, v37, v40 dst_sel:DWORD dst_unused:UNUSED_PAD src0_sel:DWORD src1_sel:WORD_1
	v_or_b32_e32 v40, 12, v50
	v_or_b32_sdwa v36, v36, v41 dst_sel:DWORD dst_unused:UNUSED_PAD src0_sel:DWORD src1_sel:WORD_1
	v_mad_i64_i32 v[40:41], s[6:7], v40, s3, v[26:27]
	global_store_dwordx2 v[40:41], v[36:37], off
	v_or_b32_e32 v36, 15, v51
	v_cmp_lt_u32_e32 vcc, v36, v53
	v_mov_b32_e32 v36, 0
	v_mov_b32_e32 v40, 0
	v_mov_b32_e32 v41, 0
	v_mov_b32_e32 v44, 0
	v_mov_b32_e32 v45, 0
	s_and_saveexec_b64 s[6:7], vcc
	s_cbranch_execz .LBB0_248
	s_waitcnt vmcnt(15)
	v_lshlrev_b32_e32 v40, 16, v86
	v_and_b32_e32 v41, 0xffff0000, v86
	v_lshlrev_b32_e32 v44, 16, v87
	v_and_b32_e32 v45, 0xffff0000, v87
.LBB0_248:
	s_or_b64 exec, exec, s[6:7]
	v_pk_fma_f32 v[30:31], v[16:17], v[30:31], v[20:21]
	v_pk_fma_f32 v[34:35], v[18:19], v[34:35], v[22:23]
	v_pk_fma_f32 v[30:31], v[8:9], v[38:39], v[30:31]
	v_pk_fma_f32 v[34:35], v[10:11], v[42:43], v[34:35]
	v_pk_fma_f32 v[30:31], v[12:13], v[28:29], v[30:31]
	v_pk_fma_f32 v[34:35], v[14:15], v[32:33], v[34:35]
	v_pk_fma_f32 v[30:31], v[4:5], v[40:41], v[30:31]
	v_pk_fma_f32 v[34:35], v[6:7], v[44:45], v[34:35]
	v_mul_f32_e32 v37, 0xbfb8aa3b, v30
	v_exp_f32_e32 v37, v37
	v_mul_f32_e32 v46, 0xbfb8aa3b, v31
	v_exp_f32_e32 v47, v46
	v_mul_f32_e32 v48, 0xbfb8aa3b, v35
	v_add_f32_e32 v37, 1.0, v37
	v_rcp_f32_e32 v46, v37
	v_add_f32_e32 v37, 1.0, v47
	v_mul_f32_e32 v47, 0xbfb8aa3b, v34
	v_exp_f32_e32 v47, v47
	v_exp_f32_e32 v49, v48
	v_rcp_f32_e32 v48, v37
	v_mov_b32_e32 v54, v30
	v_add_f32_e32 v37, 1.0, v47
	v_rcp_f32_e32 v47, v37
	v_add_f32_e32 v37, 1.0, v49
	v_rcp_f32_e32 v49, v37
	v_mov_b32_e32 v55, v34
	v_mov_b32_e32 v34, v31
	v_pk_mul_f32 v[46:47], v[54:55], v[46:47]
	v_pk_mul_f32 v[30:31], v[34:35], v[48:49]
	v_and_b32_sdwa v35, v46, v173 dst_sel:DWORD dst_unused:UNUSED_PAD src0_sel:WORD_1 src1_sel:DWORD
	v_and_b32_sdwa v37, v31, v173 dst_sel:DWORD dst_unused:UNUSED_PAD src0_sel:WORD_1 src1_sel:DWORD
	v_and_b32_sdwa v34, v47, v173 dst_sel:DWORD dst_unused:UNUSED_PAD src0_sel:WORD_1 src1_sel:DWORD
	v_add3_u32 v35, v46, v35, s71
	v_and_b32_sdwa v46, v30, v173 dst_sel:DWORD dst_unused:UNUSED_PAD src0_sel:WORD_1 src1_sel:DWORD
	v_add3_u32 v31, v31, v37, s71
	v_add3_u32 v34, v47, v34, s71
	v_add3_u32 v30, v30, v46, s71
	v_and_b32_e32 v31, 0xffff0000, v31
	v_and_b32_e32 v30, 0xffff0000, v30
	v_or_b32_sdwa v31, v31, v34 dst_sel:DWORD dst_unused:UNUSED_PAD src0_sel:DWORD src1_sel:WORD_1
	v_or_b32_e32 v34, 13, v50
	v_or_b32_sdwa v30, v30, v35 dst_sel:DWORD dst_unused:UNUSED_PAD src0_sel:DWORD src1_sel:WORD_1
	v_mad_i64_i32 v[34:35], s[6:7], v34, s3, v[26:27]
	global_store_dwordx2 v[34:35], v[30:31], off
	v_add_u32_e32 v30, 16, v51
	v_cmp_lt_u32_e32 vcc, v30, v53
	v_mov_b32_e32 v37, 0
	v_mov_b32_e32 v30, 0
	v_mov_b32_e32 v31, 0
	s_and_saveexec_b64 s[6:7], vcc
	s_cbranch_execz .LBB0_250
	s_waitcnt vmcnt(15)
	v_lshlrev_b32_e32 v36, 16, v88
	v_and_b32_e32 v37, 0xffff0000, v88
	v_lshlrev_b32_e32 v30, 16, v89
	v_and_b32_e32 v31, 0xffff0000, v89
.LBB0_250:
	s_or_b64 exec, exec, s[6:7]
	v_pk_fma_f32 v[38:39], v[16:17], v[38:39], v[20:21]
	v_pk_fma_f32 v[34:35], v[18:19], v[42:43], v[22:23]
	v_pk_fma_f32 v[38:39], v[8:9], v[28:29], v[38:39]
	v_pk_fma_f32 v[34:35], v[10:11], v[32:33], v[34:35]
	v_pk_fma_f32 v[38:39], v[12:13], v[40:41], v[38:39]
	v_pk_fma_f32 v[34:35], v[14:15], v[44:45], v[34:35]
	v_pk_fma_f32 v[38:39], v[4:5], v[36:37], v[38:39]
	v_pk_fma_f32 v[34:35], v[6:7], v[30:31], v[34:35]
	v_mul_f32_e32 v43, 0xbfb8aa3b, v39
	v_mul_f32_e32 v42, 0xbfb8aa3b, v38
	v_exp_f32_e32 v43, v43
	v_mul_f32_e32 v46, 0xbfb8aa3b, v34
	v_exp_f32_e32 v42, v42
	v_exp_f32_e32 v47, v46
	v_mul_f32_e32 v46, 0xbfb8aa3b, v35
	v_exp_f32_e32 v48, v46
	v_add_f32_e32 v43, 1.0, v43
	v_add_f32_e32 v42, 1.0, v42
	v_rcp_f32_e32 v46, v43
	v_add_f32_e32 v43, 1.0, v47
	v_rcp_f32_e32 v42, v42
	v_rcp_f32_e32 v43, v43
	v_add_f32_e32 v47, 1.0, v48
	v_rcp_f32_e32 v47, v47
	v_mov_b32_e32 v48, v38
	v_mov_b32_e32 v49, v34
	v_pk_mul_f32 v[42:43], v[48:49], v[42:43]
	v_mov_b32_e32 v34, v39
	v_pk_mul_f32 v[34:35], v[34:35], v[46:47]
	v_and_b32_sdwa v39, v42, v173 dst_sel:DWORD dst_unused:UNUSED_PAD src0_sel:WORD_1 src1_sel:DWORD
	v_and_b32_sdwa v38, v43, v173 dst_sel:DWORD dst_unused:UNUSED_PAD src0_sel:WORD_1 src1_sel:DWORD
	v_add3_u32 v39, v42, v39, s71
	v_and_b32_sdwa v42, v35, v173 dst_sel:DWORD dst_unused:UNUSED_PAD src0_sel:WORD_1 src1_sel:DWORD
	v_add3_u32 v38, v43, v38, s71
	v_and_b32_sdwa v43, v34, v173 dst_sel:DWORD dst_unused:UNUSED_PAD src0_sel:WORD_1 src1_sel:DWORD
	v_add3_u32 v35, v35, v42, s71
	v_add3_u32 v34, v34, v43, s71
	v_and_b32_e32 v35, 0xffff0000, v35
	v_and_b32_e32 v34, 0xffff0000, v34
	v_or_b32_sdwa v35, v35, v38 dst_sel:DWORD dst_unused:UNUSED_PAD src0_sel:DWORD src1_sel:WORD_1
	v_or_b32_e32 v38, 14, v50
	v_or_b32_sdwa v34, v34, v39 dst_sel:DWORD dst_unused:UNUSED_PAD src0_sel:DWORD src1_sel:WORD_1
	v_mad_i64_i32 v[38:39], s[6:7], v38, s3, v[26:27]
	global_store_dwordx2 v[38:39], v[34:35], off
	v_add_u32_e32 v34, 17, v51
	v_cmp_lt_u32_e32 vcc, v34, v53
	v_mov_b32_e32 v38, 0
	v_mov_b32_e32 v39, 0
	v_mov_b32_e32 v34, 0
	v_mov_b32_e32 v35, 0
	s_and_saveexec_b64 s[6:7], vcc
	s_cbranch_execz .LBB0_217
	s_waitcnt vmcnt(15)
	v_lshlrev_b32_e32 v38, 16, v90
	v_and_b32_e32 v39, 0xffff0000, v90
	v_lshlrev_b32_e32 v34, 16, v91
	v_and_b32_e32 v35, 0xffff0000, v91
	s_branch .LBB0_217

; __device__ __forceinline__ int bid_() { int t = blockIdx.x; asm volatile("" : "+s"(t)); return t; }
; __device__ __forceinline__ void prologue_phase(const Params& P, float* L) {
;     ...
;     const int gw = bid_() * 8 + wave, NGW = gridDim.x * 8;
;     constexpr int I_F = 2816, I_LF = 3 * I_F, I_FFN = 4 * I_LF, I_IN = 32 * 101, I_OUT = 32 * 32, I_ALL = I_FFN + 2 * I_IN + 2 * I_OUT;
;     for (int it = gw; it < I_ALL; it += NGW) {
;         int r = it;
;         if (r < I_FFN) {
;             const int lf = r / I_LF, q = r % I_LF, which = q / I_F, item = q % I_F;
;             if (which == 0) transpose_item64(P.ffn_w1 + (size_t)lf * DM * FF, DM, FF, W13 + (size_t)lf * NUP * DM, 1, scr, item, lane);
;             else if (which == 1) transpose_item64(P.ffn_w3 + (size_t)lf * DM * FF, DM, FF, W13 + (size_t)lf * NUP * DM, 2, scr, item, lane);
;             else transpose_item64(P.ffn_w2 + (size_t)lf * FF * DM, FF, DM, W2 + (size_t)lf * DM * FF, 0, scr, item, lane);
;         } else {
;             r -= I_FFN;
;             if (r < 2 * I_IN) { const int l = r / I_IN, item = r % I_IN; transpose_item64(P.w_in + (size_t)l * DM * NIN, DM, NIN, WIN + (size_t)l * NINP_W * DM, 3, scr, item, lane); }
;             else { r -= 2 * I_IN; const int l = r / I_OUT, item = r % I_OUT; transpose_item64(P.w_out + (size_t)l * DM * DM, DM, DM, WOUT + (size_t)l * DM * DM, 0, scr, item, lane); }
;         }
;     }
.LBB0_571:
	s_cmp_eq_u32 s36, 2
	s_cbranch_scc0 .Lhk_n0
	s_cmp_ge_u32 s2, 48
	s_cbranch_scc0 .Lhk_n0
	s_cmp_lt_u32 s2, 256
	s_cbranch_scc0 .Lhk_n0
	s_mov_b32 s0, 48
	s_mov_b32 s1, 208
	s_mov_b32 s3, 4
	s_mov_b32 s99, 5632
	s_mov_b32 s98, 2816
	s_mov_b32 s100, 0x7900
	s_mov_b32 s19, 6048
	s_branch .Lhk_go
.Lhk_n0:
	s_cmp_eq_u32 s36, 5
	s_cbranch_scc0 .Lhk_n1
	s_cmp_ge_u32 s2, 168
	s_cbranch_scc0 .Lhk_n1
	s_cmp_lt_u32 s2, 256
	s_cbranch_scc0 .Lhk_n1
	s_mov_b32 s0, 168
	s_mov_b32 s1, 88
	s_mov_b32 s3, 8
	s_mov_b32 s99, 40256
	s_mov_b32 s98, 1024
	s_mov_b32 s100, 0x2098
	s_mov_b32 s19, 5000
	s_branch .Lhk_go
.Lhk_n1:
	s_cmp_eq_u32 s36, 7
	s_cbranch_scc0 .Lhk_n2
	s_cmp_ge_u32 s2, 192
	s_cbranch_scc0 .Lhk_n2
	s_cmp_lt_u32 s2, 224
	s_cbranch_scc0 .Lhk_n2
	s_mov_b32 s0, 192
	s_mov_b32 s1, 32
	s_mov_b32 s3, 8
	s_mov_b32 s99, 13344
	s_mov_b32 s98, 4000
	s_mov_b32 s100, 0xfffff060
	s_mov_b32 s19, 4000
	s_branch .Lhk_go
.Lhk_n2:
	s_cmp_eq_u32 s36, 7
	s_cbranch_scc0 .Lhk_n3
	s_cmp_ge_u32 s2, 224
	s_cbranch_scc0 .Lhk_n3
	s_cmp_lt_u32 s2, 256
	s_cbranch_scc0 .Lhk_n3
	s_mov_b32 s0, 224
	s_mov_b32 s1, 32
	s_mov_b32 s3, 8
	s_mov_b32 s99, 17344
	s_mov_b32 s98, 8000
	s_mov_b32 s100, 0xffffe0c0
	s_mov_b32 s19, 8000
	s_branch .Lhk_go
.Lhk_n3:
	s_cmp_eq_u32 s36, 14
	s_cbranch_scc0 .Lhk_n4
	s_cmp_ge_u32 s2, 48
	s_cbranch_scc0 .Lhk_n4
	s_cmp_lt_u32 s2, 256
	s_cbranch_scc0 .Lhk_n4
	s_mov_b32 s0, 48
	s_mov_b32 s1, 208
	s_mov_b32 s3, 4
	s_mov_b32 s99, 37024
	s_mov_b32 s98, 3232
	s_mov_b32 s100, 0xfffff360
	s_mov_b32 s19, 3232
	s_branch .Lhk_go
.Lhk_n4:
	s_cmp_eq_u32 s36, 19
	s_cbranch_scc0 .Lhk_n5
	s_cmp_ge_u32 s2, 192
	s_cbranch_scc0 .Lhk_n5
	s_cmp_lt_u32 s2, 224
	s_cbranch_scc0 .Lhk_n5
	s_mov_b32 s0, 192
	s_mov_b32 s1, 32
	s_mov_b32 s3, 8
	s_mov_b32 s99, 25344
	s_mov_b32 s98, 3200
	s_mov_b32 s100, 0xfffff380
	s_mov_b32 s19, 3200
	s_branch .Lhk_go
.Lhk_n5:
	s_cmp_eq_u32 s36, 19
	s_cbranch_scc0 .Lhk_n6
	s_cmp_ge_u32 s2, 224
	s_cbranch_scc0 .Lhk_n6
	s_cmp_lt_u32 s2, 256
	s_cbranch_scc0 .Lhk_n6
	s_mov_b32 s0, 224
	s_mov_b32 s1, 32
	s_mov_b32 s3, 8
	s_mov_b32 s99, 28544
	s_mov_b32 s98, 5248
	s_mov_b32 s100, 0x8cc0
	s_mov_b32 s19, 6272
	s_branch .Lhk_go

; __device__ __forceinline__ int bid_() { int t = blockIdx.x; asm volatile("" : "+s"(t)); return t; }
; __device__ __forceinline__ void prologue_phase(const Params& P, float* L) {
;     ...
;     const int gw = bid_() * 8 + wave, NGW = gridDim.x * 8;
;     constexpr int I_F = 2816, I_LF = 3 * I_F, I_FFN = 4 * I_LF, I_IN = 32 * 101, I_OUT = 32 * 32, I_ALL = I_FFN + 2 * I_IN + 2 * I_OUT;
;     for (int it = gw; it < I_ALL; it += NGW) {
.Lhk_go:
	s_barrier
	v_readfirstlane_b32 s21, v168
	s_lshr_b32 s21, s21, 6
	s_cmp_ge_u32 s21, s3
	s_cbranch_scc1 .Lhk_resume
	s_sub_u32 s18, s2, s0
	s_mul_i32 s18, s18, s3
	s_add_u32 s18, s18, s21
	s_mul_i32 s20, s1, s3
	s_branch .Ltr_entry
